# Attention item prologues (MLA and memory): K/V tile-0 loads no longer wait for the Q / rotary / statistics loads to return first (one round trip instead of two)
# baseline (speedup 1.0000x reference)
.LBB0_1421:
	s_and_b64 s[8:9], s[70:71], exec
	s_cselect_b32 s35, s84, s83
	s_or_b32 s68, s30, s35
	s_mul_hi_u32 s9, s68, 0x600
	s_mul_i32 s10, s31, 0x600
	s_mul_i32 s8, s68, 0x600
	s_add_i32 s9, s9, s10
	s_mov_b32 s69, s31
	s_add_u32 s8, s85, s8
	s_addc_u32 s9, s86, s9
	s_lshl_b64 s[10:11], s[68:69], 6
	s_add_u32 s12, s76, s10
	s_addc_u32 s13, s77, s11
	s_add_u32 s22, s78, s10
	s_addc_u32 s23, s79, s11
	v_mov_b32_e32 v60, v220
	s_add_u32 s10, s80, s10
	s_addc_u32 s11, s81, s11
	v_readfirstlane_b32 s67, v60
	s_ashr_i32 s74, s67, 1
	v_mov_b32_e32 v0, s74
	v_bfi_b32 v124, s28, v0, v60
	v_ashrrev_i32_e32 v125, 31, v124
	v_bfe_u32 v82, v60, 5, 1
	v_mov_b64_e32 v[0:1], s[8:9]
	v_lshlrev_b64 v[4:5], 6, v[124:125]
	v_mad_i64_i32 v[0:1], s[8:9], v124, s26, v[0:1]
	v_lshlrev_b32_e32 v126, 4, v82
	v_mov_b32_e32 v127, v97
	v_lshl_add_u64 v[6:7], s[12:13], 0, v[4:5]
	v_lshl_add_u64 v[8:9], s[22:23], 0, v[4:5]
	v_lshl_add_u64 v[4:5], s[10:11], 0, v[4:5]
	v_lshl_add_u64 v[36:37], v[0:1], 0, v[126:127]
	v_lshl_add_u64 v[8:9], v[8:9], 0, v[126:127]
	v_lshl_add_u64 v[10:11], v[4:5], 0, v[126:127]
	global_load_dwordx4 v[24:27], v[36:37], off offset:96
	global_load_dwordx4 v[12:15], v[36:37], off offset:128
	global_load_dwordx4 v[0:3], v[36:37], off offset:160
	flat_load_dwordx4 v[44:47], v[6:7]
	global_load_dwordx4 v[48:51], v[6:7], off offset:16
	global_load_dwordx4 v[28:31], v[36:37], off offset:64
	global_load_dwordx4 v[32:35], v[36:37], off offset:32
	global_load_dwordx4 v[40:43], v[6:7], off offset:32
	global_load_dwordx4 v[16:19], v[8:9], off
	global_load_dwordx4 v[20:23], v[10:11], off
	s_nop 0
	global_load_dwordx4 v[4:7], v[8:9], off offset:32
	s_nop 0
	global_load_dwordx4 v[8:11], v[10:11], off offset:32
	v_ashrrev_i32_e32 v61, 31, v60
	v_lshl_add_u64 v[76:77], v[60:61], 4, s[50:51]
	global_load_dwordx4 v[36:39], v[36:37], off
	s_nop 0
	global_load_dwordx4 v[52:55], v[76:77], off
	v_mov_b32_e32 v96, v97
	s_movk_i32 s8, 0x100
	v_mov_b32_e32 v98, v97
	v_mov_b32_e32 v99, v97
	v_mov_b64_e32 v[64:65], v[96:97]
	v_cmp_gt_i32_e64 s[8:9], s8, v60
	v_mov_b64_e32 v[66:67], v[98:99]
	s_and_saveexec_b64 s[10:11], s[8:9]
	s_cbranch_execz .LBB0_1423
	v_add_co_u32_e32 v56, vcc, 0x2000, v76
	s_nop 1
	v_addc_co_u32_e32 v57, vcc, 0, v77, vcc
	global_load_dwordx4 v[64:67], v[56:57], off

.LBB0_1539:
	s_ashr_i32 s6, s54, 6
	s_ashr_i32 s7, s6, 31
	s_lshl_b32 s8, s54, 17
	s_and_b32 s10, s8, 0x1e0000
	s_lshl_b64 s[8:9], s[6:7], 21
	s_or_b32 s8, s8, s10
	s_bfe_u32 s35, s54, 0x20004
	s_lshl_b64 s[24:25], s[8:9], 1
	s_add_u32 s7, s17, s24
	s_addc_u32 s9, s40, s25
	s_lshl_b32 s8, s35, 8
	s_add_u32 s8, s7, s8
	s_addc_u32 s9, s9, 0
	s_lshl_b32 s6, s6, 2
	s_add_i32 s6, s6, s1
	s_or_b32 s6, s6, s35
	s_ashr_i32 s7, s6, 31
	s_lshl_b64 s[10:11], s[6:7], 16
	v_mov_b32_e32 v8, v220
	s_add_u32 s6, s42, s10
	s_addc_u32 s7, s43, s11
	v_readfirstlane_b32 s22, v8
	s_ashr_i32 s22, s22, 1
	v_bfe_u32 v18, v8, 5, 1
	v_mov_b32_e32 v0, s22
	v_bfi_b32 v0, s28, v0, v8
	v_ashrrev_i32_e32 v1, 31, v0
	v_lshlrev_b64 v[164:165], 10, v[0:1]
	v_lshl_add_u64 v[0:1], s[8:9], 0, v[164:165]
	v_lshlrev_b32_e32 v16, 4, v18
	v_mov_b32_e32 v17, v97
	v_lshl_add_u64 v[0:1], v[0:1], 0, v[16:17]
	global_load_dwordx4 v[100:103], v[0:1], off offset:32
	global_load_dwordx4 v[104:107], v[0:1], off offset:64
	global_load_dwordx4 v[108:111], v[0:1], off offset:96
	global_load_dwordx4 v[112:115], v[0:1], off offset:128
	global_load_dwordx4 v[116:119], v[0:1], off offset:160
	global_load_dwordx4 v[120:123], v[0:1], off offset:192
	global_load_dwordx4 v[124:127], v[0:1], off offset:224
	v_ashrrev_i32_e32 v9, 31, v8
	v_lshl_add_u64 v[10:11], v[8:9], 4, s[6:7]
	global_load_dwordx4 v[128:131], v[0:1], off
	s_nop 0
	global_load_dwordx4 v[0:3], v[10:11], off
	v_mov_b32_e32 v98, v97
	v_mov_b32_e32 v99, v97
	s_movk_i32 s8, 0x200
	v_mov_b32_e32 v96, v97
	v_mov_b64_e32 v[134:135], v[98:99]
	v_cmp_lt_i32_e64 s[6:7], s60, v8
	v_cmp_gt_i32_e64 s[8:9], s8, v8
	v_mov_b64_e32 v[132:133], v[96:97]
	s_and_saveexec_b64 s[30:31], s[8:9]
	s_cbranch_execz .LBB0_1541
	v_add_co_u32_e32 v4, vcc, 0x2000, v10
	s_nop 1
	v_addc_co_u32_e32 v5, vcc, 0, v11, vcc
	global_load_dwordx4 v[132:135], v[4:5], off
